# v53_q3
# baseline (speedup 1.0000x reference)
; __global__ void __launch_bounds__(512) fwd(Args a_) {
;     ...
;         } else if (PHM(2) && sp == 2) { PHASE_PROLOGUE
;             if ((G & 7) == 0 && G >= 128) { if (bx < 128) compress_item(c, a, L, (bx & 7) * 16 + (bx >> 3), lds, wave, lane, tid); }
;             else for (int it = bx; it < 128; it += G) compress_item(c, a, L, it, lds, wave, lane, tid);
;             {
;                 const int xq = (G & 7) == 0 ? (bx & 7) : 0, nxq = (G & 7) == 0 ? 8 : 1;
;                 unsigned* qctr = (unsigned*)(a.ws + WS_CTL) + 8192 + 64 * (16 + 8 * L + xq);
;                 const int nsb = 2048 / nxq, nsw = 4096 / nxq;
;                 for (;;) {
;                     int li = 0; if (lane == 0) li = (int)atomicAdd(qctr, 1u);
;                     li = __builtin_amdgcn_readfirstlane(li);
;                     if (li >= nsb + nsw) break;
;                     const int it = li < nsb ? xq * nsb + li : 2048 + xq * nsw + (li - nsb);
;                     if (it < 2048) sb_item(c, 511 - (it >> 2), it & 3, lane);
;                     else { const int k = it - 2048; swa_item(c, a.in[3] + L * 8, k >> 3, k & 7, lane); }
;                 }
;             }
;         } else if (PHM(3) && sp == 3) { PHASE_PROLOGUE
;             const unsigned* kmx = (const unsigned*)(a.ws + WS_CTL) + 8192 + 64 * (8 + 2 * L);
;             const float kb0 = 8.f * 1.01f * __uint_as_float(kmx[0]), kb1 = 8.f * 1.01f * __uint_as_float(kmx[64]);
;             const int gwx = ((G & 7) == 0 ? (bx & 7) * (G >> 3) + (bx >> 3) : bx) * 8 + wave;
;             for (int k = gwx; k < 2048; k += NGW) { nsa_item8(c, 2047 - (k >> 1), 1 - (k & 1), lds, wave, lane, (k & 1) ? kb0 : kb1); nsa_item8(c, k >> 1, k & 1, lds, wave, lane, (k & 1) ? kb1 : kb0); }
;         } else if (PHM(4) && sp == 4) { PHASE_PROLOGUE
.LBB0_158:
	s_and_b64 vcc, exec, s[6:7]
	s_cbranch_vccz .LBB0_1228
	s_cmp_gt_i32 s44, 1
	s_mov_b64 s[6:7], -1
	s_cbranch_scc0 .LBB0_1173
	s_cmp_gt_i32 s44, 2
	v_writelane_b32 v244, s84, 28
	s_cbranch_scc0 .LBB0_1098
	v_readlane_b32 s101, v244, 7
	v_readlane_b32 s84, v244, 28
	s_nop 1
	s_bitcmp1_b32 s101, 0
	s_cbranch_scc0 .Lcq_p3_cont
	v_writelane_b32 v246, 3, 1
	s_lshl_b32 s100, s84, 1
	s_add_i32 s100, s100, 9
	s_branch .Lcq_entry
